# plus attention cross-half running-max exchange via v_permlane32_swap instead of LDS bpermute
# speedup vs baseline: 1.0092x; 1.0092x over previous
; #define MFMA(a, b, c) __builtin_amdgcn_mfma_f32_32x32x16_bf16((a), (b), (c), 0, 0, 0)
; template <int DQ, bool MASK>
; DI void attn_phase(const Params& p, unsigned char* smem, float cexp) {
;     ...
;     for (int kt = 0; kt < ntile_block; ++kt) {
;       __syncthreads();
;       {
;         constexpr int CPR = DQ / 8;
; #pragma unroll
;         for (int i = 0; i < DQ / 32; ++i) {
;           int c = tid + 256 * i;
;           int row = c / CPR, cc = c % CPR;
;           uint4 v = *(const uint4*)(Kb + ((size_t)bh * 2048 + kt * 64 + row) * DQ + cc * 8);
;           *(uint4*)(Ks + row * KST + cc * 8) = v;
;         }
; #pragma unroll
;         for (int i = 0; i < 4; ++i) {
;           int c = tid + 256 * i;
;           int d = c >> 3, cc = c & 7;
;           uint4 v = *(const uint4*)(Vt + (((size_t)bh * 32 + kt) * 128 + d) * 64 + cc * 8);
;           uint2* dp = (uint2*)(Vs + d * VST + cc * 8);
;           dp[0] = make_uint2(v.x, v.y);
;           dp[1] = make_uint2(v.z, v.w);
;         }
;       }
;       __syncthreads();
;       if (kt < my_nt) {
;         f32x16 sa[2];
; #pragma unroll
;         for (int u = 0; u < 2; ++u) {
; #pragma unroll
;           for (int i = 0; i < 16; ++i) sa[u][i] = 0.f;
; #pragma unroll
;           for (int s = 0; s < DQ / 16; ++s) {
;             bf16x8 a = *(const bf16x8*)(Ks + (32 * u + r) * KST + 16 * s + 8 * g);
;             sa[u] = MFMA(a, qf[s], sa[u]);
;           }
;         }
;         if (MASK) {
;           u64 mw = mask[tok * 32 + kt] >> (4 * g);
;           const u32 mlo = (u32)mw, mhi = (u32)(mw >> 32);
; #pragma unroll
;           for (int i = 0; i < 16; ++i) {
;             const u32 bit = 1u << ((i & 3) + 8 * (i >> 2));
;             if (!(mlo & bit)) sa[0][i] = -INFINITY;
;             if (!(mhi & bit)) sa[1][i] = -INFINITY;
;           }
;         }
;         float mx = -INFINITY;
; #pragma unroll
;         for (int u = 0; u < 2; ++u)
; #pragma unroll
;           for (int i = 0; i < 16; ++i) mx = fmaxf(mx, sa[u][i]);
;         mx = fmaxf(mx, __shfl_xor(mx, 32));
.LBB0_422:
	v_lshl_add_u64 v[2:3], s[22:23], 0, v[206:207]
	v_lshl_add_u64 v[6:7], s[22:23], 0, v[208:209]
	v_lshl_add_u64 v[10:11], s[22:23], 0, v[210:211]
	v_lshl_add_u64 v[14:15], s[22:23], 0, v[212:213]
	s_waitcnt vmcnt(63) expcnt(7) lgkmcnt(15)
	s_barrier
	global_load_dwordx4 v[2:5], v[2:3], off
	s_nop 0
	global_load_dwordx4 v[6:9], v[6:7], off
	s_nop 0
	global_load_dwordx4 v[10:13], v[10:11], off
	s_nop 0
	global_load_dwordx4 v[80:83], v[14:15], off
	v_lshl_add_u64 v[14:15], s[22:23], 0, v[214:215]
	v_lshl_add_u64 v[88:89], s[22:23], 0, v[216:217]
	global_load_dwordx4 v[84:87], v[14:15], off
	s_nop 0
	global_load_dwordx4 v[88:91], v[88:89], off
	v_lshl_add_u64 v[14:15], s[22:23], 0, v[204:205]
	v_add_co_u32_e32 v14, vcc, s62, v14
	v_lshl_add_u64 v[92:93], s[22:23], 0, v[202:203]
	s_nop 0
	v_addc_co_u32_e32 v15, vcc, 0, v15, vcc
	v_add_co_u32_e32 v96, vcc, s62, v92
	v_lshl_add_u64 v[100:101], s[22:23], 0, v[198:199]
	s_nop 0
	v_addc_co_u32_e32 v97, vcc, 0, v93, vcc
	global_load_dwordx4 v[92:95], v[14:15], off
	s_nop 0
	global_load_dwordx4 v[96:99], v[96:97], off
	v_lshl_add_u64 v[14:15], s[22:23], 0, v[200:201]
	v_add_co_u32_e32 v14, vcc, s62, v14
	s_nop 1
	v_addc_co_u32_e32 v15, vcc, 0, v15, vcc
	v_add_co_u32_e32 v104, vcc, 0xe000000, v100
	s_nop 1
	v_addc_co_u32_e32 v105, vcc, 0, v101, vcc
	global_load_dwordx4 v[100:103], v[14:15], off
	s_nop 0
	global_load_dwordx4 v[104:107], v[104:105], off
	v_cmp_lt_i32_e32 vcc, s54, v197
	s_waitcnt vmcnt(9)
	ds_write_b128 v229, v[2:5]
	s_waitcnt vmcnt(8)
	ds_write_b128 v230, v[6:9]
	s_waitcnt vmcnt(7)
	ds_write_b128 v231, v[10:13]
	s_waitcnt vmcnt(6)
	ds_write_b128 v232, v[80:83]
	s_waitcnt vmcnt(5)
	ds_write_b128 v233, v[84:87]
	s_waitcnt vmcnt(4)
	ds_write_b128 v234, v[88:91]
	s_waitcnt vmcnt(3)
	ds_write2_b64 v235, v[92:93], v[94:95] offset1:1
	s_waitcnt vmcnt(2)
	ds_write2_b64 v236, v[96:97], v[98:99] offset1:1
	s_waitcnt vmcnt(1)
	ds_write2_b64 v237, v[100:101], v[102:103] offset1:1
	s_waitcnt vmcnt(0)
	ds_write2_b64 v238, v[104:105], v[106:107] offset1:1
	s_waitcnt lgkmcnt(0)
	s_barrier
	s_and_saveexec_b64 s[12:13], vcc
	s_cbranch_execz .LBB0_421
	ds_read_b128 v[2:5], v239
	ds_read_b128 v[6:9], v239 offset:12800
	ds_read_b128 v[244:247], v239 offset:32
	ds_read_b128 v[248:251], v239 offset:12832
	s_waitcnt lgkmcnt(3)
	v_mfma_f32_32x32x16_bf16 v[96:111], v[2:5], v[112:115], 0
	ds_read_b128 v[2:5], v239 offset:64
	s_waitcnt lgkmcnt(3)
	v_mfma_f32_32x32x16_bf16 v[80:95], v[6:9], v[112:115], 0
	ds_read_b128 v[6:9], v239 offset:12864
	s_waitcnt lgkmcnt(3)
	v_mfma_f32_32x32x16_bf16 v[96:111], v[244:247], v[116:119], v[96:111]
	ds_read_b128 v[244:247], v239 offset:96
	s_waitcnt lgkmcnt(3)
	v_mfma_f32_32x32x16_bf16 v[80:95], v[248:251], v[116:119], v[80:95]
	ds_read_b128 v[248:251], v239 offset:12896
	s_waitcnt lgkmcnt(3)
	v_mfma_f32_32x32x16_bf16 v[96:111], v[2:5], v[120:123], v[96:111]
	ds_read_b128 v[2:5], v239 offset:128
	s_waitcnt lgkmcnt(3)
	v_mfma_f32_32x32x16_bf16 v[80:95], v[6:9], v[120:123], v[80:95]
	ds_read_b128 v[6:9], v239 offset:12928
	s_waitcnt lgkmcnt(3)
	v_mfma_f32_32x32x16_bf16 v[96:111], v[244:247], v[124:127], v[96:111]
	ds_read_b128 v[244:247], v239 offset:160
	s_waitcnt lgkmcnt(3)
	v_mfma_f32_32x32x16_bf16 v[80:95], v[248:251], v[124:127], v[80:95]
	ds_read_b128 v[248:251], v239 offset:12960
	s_waitcnt lgkmcnt(3)
	v_mfma_f32_32x32x16_bf16 v[96:111], v[2:5], v[128:131], v[96:111]
	ds_read_b128 v[2:5], v239 offset:192
	s_waitcnt lgkmcnt(3)
	v_mfma_f32_32x32x16_bf16 v[80:95], v[6:9], v[128:131], v[80:95]
	ds_read_b128 v[6:9], v239 offset:12992
	s_waitcnt lgkmcnt(3)
	v_mfma_f32_32x32x16_bf16 v[96:111], v[244:247], v[132:135], v[96:111]
	ds_read_b128 v[244:247], v239 offset:224
	s_waitcnt lgkmcnt(3)
	v_mfma_f32_32x32x16_bf16 v[80:95], v[248:251], v[132:135], v[80:95]
	ds_read_b128 v[248:251], v239 offset:13024
	s_waitcnt lgkmcnt(3)
	v_mfma_f32_32x32x16_bf16 v[96:111], v[2:5], v[136:139], v[96:111]
	ds_read_b128 v[2:5], v239 offset:256
	s_waitcnt lgkmcnt(3)
	v_mfma_f32_32x32x16_bf16 v[80:95], v[6:9], v[136:139], v[80:95]
	ds_read_b128 v[6:9], v239 offset:13056
	s_waitcnt lgkmcnt(3)
	v_mfma_f32_32x32x16_bf16 v[96:111], v[244:247], v[140:143], v[96:111]
	ds_read_b128 v[244:247], v239 offset:288
	s_waitcnt lgkmcnt(3)
	v_mfma_f32_32x32x16_bf16 v[80:95], v[248:251], v[140:143], v[80:95]
	ds_read_b128 v[248:251], v239 offset:13088
	s_waitcnt lgkmcnt(3)
	v_mfma_f32_32x32x16_bf16 v[96:111], v[2:5], v[144:147], v[96:111]
	ds_read_b128 v[2:5], v239 offset:320
	s_waitcnt lgkmcnt(3)
	v_mfma_f32_32x32x16_bf16 v[80:95], v[6:9], v[144:147], v[80:95]
	ds_read_b128 v[6:9], v239 offset:13120
	s_waitcnt lgkmcnt(3)
	v_mfma_f32_32x32x16_bf16 v[96:111], v[244:247], v[148:151], v[96:111]
	ds_read_b128 v[244:247], v239 offset:352
	s_waitcnt lgkmcnt(3)
	v_mfma_f32_32x32x16_bf16 v[80:95], v[248:251], v[148:151], v[80:95]
	ds_read_b128 v[248:251], v239 offset:13152
	s_waitcnt lgkmcnt(3)
	v_mfma_f32_32x32x16_bf16 v[96:111], v[2:5], v[152:155], v[96:111]
	s_waitcnt lgkmcnt(2)
	v_mfma_f32_32x32x16_bf16 v[80:95], v[6:9], v[152:155], v[80:95]
	s_waitcnt lgkmcnt(1)
	v_mfma_f32_32x32x16_bf16 v[96:111], v[244:247], v[156:159], v[96:111]
	s_waitcnt lgkmcnt(0)
	v_mfma_f32_32x32x16_bf16 v[80:95], v[248:251], v[156:159], v[80:95]
	s_nop 7
	s_nop 3
	v_max3_f32 v1, v96, s64, v97
	v_max3_f32 v1, v1, v98, v99
	v_max3_f32 v1, v1, v100, v101
	v_max3_f32 v1, v1, v102, v103
	v_max3_f32 v1, v1, v104, v105
	v_max3_f32 v1, v1, v106, v107
	v_max3_f32 v1, v1, v108, v109
	v_max3_f32 v1, v1, v110, v111
	s_nop 1
	v_max3_f32 v1, v1, v80, v81
	v_max3_f32 v1, v1, v82, v83
	v_max3_f32 v1, v1, v84, v85
	v_max3_f32 v1, v1, v86, v87
	v_max3_f32 v1, v1, v88, v89
	v_max3_f32 v1, v1, v90, v91
	v_max3_f32 v1, v1, v92, v93
	v_max3_f32 v1, v1, v94, v95
	v_mov_b32_e32 v2, v1
	s_nop 1
	v_permlane32_swap_b32_e32 v1, v2
	s_waitcnt lgkmcnt(0)
; #define MFMA(a, b, c) __builtin_amdgcn_mfma_f32_32x32x16_bf16((a), (b), (c), 0, 0, 0)
; template <int DQ, bool MASK>
; DI void attn_phase(const Params& p, unsigned char* smem, float cexp) {
;     ...
;         float mnew = fmaxf(m, mx);
;         float muse = (mnew == -INFINITY) ? 0.f : mnew;
;         float alpha = __builtin_amdgcn_exp2f((m - muse) * cexp);
;         m = mnew;
;         float ps = 0.f;
; #pragma unroll
;         for (int u = 0; u < 2; ++u)
; #pragma unroll
;           for (int i = 0; i < 16; ++i) {
;             float pv = __builtin_amdgcn_exp2f((sa[u][i] - muse) * cexp);
;             ps += pv;
;             sa[u][i] = pv;
;           }
;         l = l * alpha + ps;
; #pragma unroll
;         for (int j = 0; j < 4; ++j)
; #pragma unroll
;           for (int i = 0; i < 16; ++i) o[j][i] *= alpha;
; #pragma unroll
;         for (int u = 0; u < 2; ++u)
; #pragma unroll
;           for (int s2 = 0; s2 < 2; ++s2) {
;             uint4 pp;
;             pp.x = pack2(sa[u][8 * s2 + 0], sa[u][8 * s2 + 1]);
;             pp.y = pack2(sa[u][8 * s2 + 2], sa[u][8 * s2 + 3]);
;             pp.z = pack2(sa[u][8 * s2 + 4], sa[u][8 * s2 + 5]);
;             pp.w = pack2(sa[u][8 * s2 + 6], sa[u][8 * s2 + 7]);
;             bf16x8 pf = __builtin_bit_cast(bf16x8, pp);
; #pragma unroll
;             for (int dt = 0; dt < 4; ++dt) {
;               const bf16* vp = Vs + (32 * dt + r) * VST + 32 * u + 16 * s2 + 4 * g;
;               s16x4 lo = *(const s16x4*)vp;
;               s16x4 hi = *(const s16x4*)(vp + 8);
;               bf16x8 vf = __builtin_shufflevector(lo, hi, 0, 1, 2, 3, 4, 5, 6, 7);
;               o[dt] = MFMA(vf, pf, o[dt]);
;             }
;           }
	v_max3_f32 v1, v242, v1, v2
	v_cmp_neq_f32_e32 vcc, s64, v1
	s_nop 1
	v_cndmask_b32_e32 v3, 0, v1, vcc
	v_sub_f32_e32 v5, v100, v3
	v_mul_f32_e32 v5, 0x3dd53b94, v5
	v_exp_f32_e32 v12, v5
	v_sub_f32_e32 v5, v101, v3
	v_mul_f32_e32 v5, 0x3dd53b94, v5
	v_sub_f32_e32 v4, v96, v3
	v_exp_f32_e32 v13, v5
	v_sub_f32_e32 v5, v102, v3
	v_mul_f32_e32 v4, 0x3dd53b94, v4
	v_mul_f32_e32 v5, 0x3dd53b94, v5
	v_exp_f32_e32 v8, v4
	v_sub_f32_e32 v4, v97, v3
	v_exp_f32_e32 v14, v5
	v_sub_f32_e32 v5, v103, v3
	v_mul_f32_e32 v4, 0x3dd53b94, v4
	v_mul_f32_e32 v5, 0x3dd53b94, v5
	v_exp_f32_e32 v9, v4
	v_sub_f32_e32 v4, v98, v3
	v_exp_f32_e32 v15, v5
	v_sub_f32_e32 v5, v104, v3
	v_mul_f32_e32 v4, 0x3dd53b94, v4
	v_mul_f32_e32 v5, 0x3dd53b94, v5
	v_exp_f32_e32 v10, v4
	v_sub_f32_e32 v4, v99, v3
	v_exp_f32_e32 v96, v5
	v_sub_f32_e32 v5, v105, v3
	v_mul_f32_e32 v4, 0x3dd53b94, v4
	v_mul_f32_e32 v5, 0x3dd53b94, v5
	v_exp_f32_e32 v11, v4
	v_exp_f32_e32 v97, v5
	v_sub_f32_e32 v5, v106, v3
	v_add_f32_e32 v4, 0, v8
	v_mul_f32_e32 v5, 0x3dd53b94, v5
	v_add_f32_e32 v4, v9, v4
	v_exp_f32_e32 v98, v5
	v_sub_f32_e32 v5, v107, v3
	v_add_f32_e32 v4, v10, v4
	v_mul_f32_e32 v5, 0x3dd53b94, v5
	v_add_f32_e32 v4, v11, v4
	v_exp_f32_e32 v99, v5
	v_sub_f32_e32 v5, v108, v3
	v_add_f32_e32 v4, v12, v4
	v_mul_f32_e32 v5, 0x3dd53b94, v5
	v_add_f32_e32 v4, v13, v4
	v_exp_f32_e32 v100, v5
	v_sub_f32_e32 v5, v109, v3
	v_add_f32_e32 v4, v14, v4
	v_mul_f32_e32 v5, 0x3dd53b94, v5
	v_add_f32_e32 v4, v15, v4
	v_exp_f32_e32 v101, v5
	v_sub_f32_e32 v5, v110, v3
	v_add_f32_e32 v4, v96, v4
	v_mul_f32_e32 v5, 0x3dd53b94, v5
	v_add_f32_e32 v4, v97, v4
	v_exp_f32_e32 v102, v5
	v_sub_f32_e32 v5, v111, v3
	v_add_f32_e32 v4, v98, v4
	v_mul_f32_e32 v5, 0x3dd53b94, v5
	v_add_f32_e32 v4, v99, v4
	v_exp_f32_e32 v103, v5
	v_add_f32_e32 v4, v100, v4
	v_add_f32_e32 v4, v101, v4
	v_add_f32_e32 v4, v102, v4
	v_add_f32_e32 v104, v103, v4
	v_sub_f32_e32 v4, v80, v3
	v_mul_f32_e32 v4, 0x3dd53b94, v4
	v_exp_f32_e32 v80, v4
	v_sub_f32_e32 v4, v81, v3
	v_mul_f32_e32 v4, 0x3dd53b94, v4
	v_add_u32_e32 v105, 0x6000, v240
	v_exp_f32_e32 v81, v4
	ds_read2_b64 v[4:7], v105 offset0:128 offset1:130
	v_sub_f32_e32 v2, v242, v3
	v_mul_f32_e32 v2, 0x3dd53b94, v2
	v_exp_f32_e32 v2, v2
	v_add_u32_e32 v106, 0x7000, v240
	v_cvt_pk_bf16_f32 v8, v8, v9
	v_cvt_pk_bf16_f32 v9, v10, v11
	v_cvt_pk_bf16_f32 v10, v12, v13
	v_cvt_pk_bf16_f32 v11, v14, v15
	ds_read2_b64 v[12:15], v106 offset0:160 offset1:162
	v_pk_mul_f32 v[78:79], v[78:79], v[2:3] op_sel_hi:[1,0]
	v_pk_mul_f32 v[76:77], v[76:77], v[2:3] op_sel_hi:[1,0]
	v_pk_mul_f32 v[74:75], v[74:75], v[2:3] op_sel_hi:[1,0]
	v_pk_mul_f32 v[72:73], v[72:73], v[2:3] op_sel_hi:[1,0]
	v_pk_mul_f32 v[70:71], v[70:71], v[2:3] op_sel_hi:[1,0]
	v_pk_mul_f32 v[68:69], v[68:69], v[2:3] op_sel_hi:[1,0]
	v_pk_mul_f32 v[66:67], v[66:67], v[2:3] op_sel_hi:[1,0]
	v_pk_mul_f32 v[64:65], v[64:65], v[2:3] op_sel_hi:[1,0]
	v_add_u32_e32 v107, 0x8000, v240
	v_pk_mul_f32 v[62:63], v[62:63], v[2:3] op_sel_hi:[1,0]
	s_waitcnt lgkmcnt(1)
	v_mfma_f32_32x32x16_bf16 v[64:79], v[4:7], v[8:11], v[64:79]
	ds_read2_b64 v[4:7], v107 offset0:192 offset1:194
	v_mul_f32_e64 v60, v60, v2
	v_mul_f32_e64 v61, v61, v2
	v_mul_f32_e64 v58, v58, v2
	v_mul_f32_e64 v59, v59, v2
	v_pk_mul_f32 v[56:57], v[56:57], v[2:3] op_sel_hi:[1,0]
	v_pk_mul_f32 v[54:55], v[54:55], v[2:3] op_sel_hi:[1,0]
	v_pk_mul_f32 v[52:53], v[52:53], v[2:3] op_sel_hi:[1,0]
	v_pk_mul_f32 v[50:51], v[50:51], v[2:3] op_sel_hi:[1,0]
	v_pk_mul_f32 v[48:49], v[48:49], v[2:3] op_sel_hi:[1,0]
	v_add_u32_e32 v108, 0x9000, v240
	v_pk_mul_f32 v[46:47], v[46:47], v[2:3] op_sel_hi:[1,0]
	s_waitcnt lgkmcnt(1)
	v_mfma_f32_32x32x16_bf16 v[48:63], v[12:15], v[8:11], v[48:63]
	ds_read2_b64 v[12:15], v108 offset0:224 offset1:226
	v_mul_f32_e64 v44, v44, v2
	v_mul_f32_e64 v45, v45, v2
	v_mul_f32_e64 v42, v42, v2
	v_mul_f32_e64 v43, v43, v2
	v_pk_mul_f32 v[40:41], v[40:41], v[2:3] op_sel_hi:[1,0]
	v_pk_mul_f32 v[38:39], v[38:39], v[2:3] op_sel_hi:[1,0]
	v_pk_mul_f32 v[36:37], v[36:37], v[2:3] op_sel_hi:[1,0]
	v_pk_mul_f32 v[34:35], v[34:35], v[2:3] op_sel_hi:[1,0]
	v_pk_mul_f32 v[32:33], v[32:33], v[2:3] op_sel_hi:[1,0]
	v_pk_mul_f32 v[30:31], v[30:31], v[2:3] op_sel_hi:[1,0]
	v_pk_mul_f32 v[28:29], v[28:29], v[2:3] op_sel_hi:[1,0]
	s_waitcnt lgkmcnt(1)
; #define MFMA(a, b, c) __builtin_amdgcn_mfma_f32_32x32x16_bf16((a), (b), (c), 0, 0, 0)
; template <int DQ, bool MASK>
; DI void attn_phase(const Params& p, unsigned char* smem, float cexp) {
;     ...
; #pragma unroll
;         for (int u = 0; u < 2; ++u)
; #pragma unroll
;           for (int i = 0; i < 16; ++i) {
;             float pv = __builtin_amdgcn_exp2f((sa[u][i] - muse) * cexp);
;             ps += pv;
;             sa[u][i] = pv;
;           }
;         l = l * alpha + ps;
; #pragma unroll
;         for (int j = 0; j < 4; ++j)
; #pragma unroll
;           for (int i = 0; i < 16; ++i) o[j][i] *= alpha;
; #pragma unroll
;         for (int u = 0; u < 2; ++u)
; #pragma unroll
;           for (int s2 = 0; s2 < 2; ++s2) {
;             uint4 pp;
;             pp.x = pack2(sa[u][8 * s2 + 0], sa[u][8 * s2 + 1]);
;             pp.y = pack2(sa[u][8 * s2 + 2], sa[u][8 * s2 + 3]);
;             pp.z = pack2(sa[u][8 * s2 + 4], sa[u][8 * s2 + 5]);
;             pp.w = pack2(sa[u][8 * s2 + 6], sa[u][8 * s2 + 7]);
;             bf16x8 pf = __builtin_bit_cast(bf16x8, pp);
; #pragma unroll
;             for (int dt = 0; dt < 4; ++dt) {
;               const bf16* vp = Vs + (32 * dt + r) * VST + 32 * u + 16 * s2 + 4 * g;
;               s16x4 lo = *(const s16x4*)vp;
;               s16x4 hi = *(const s16x4*)(vp + 8);
;               bf16x8 vf = __builtin_shufflevector(lo, hi, 0, 1, 2, 3, 4, 5, 6, 7);
;               o[dt] = MFMA(vf, pf, o[dt]);
;             }
;           }
	v_mfma_f32_32x32x16_bf16 v[32:47], v[4:7], v[8:11], v[32:47]
	ds_read2_b64 v[4:7], v105 offset0:132 offset1:134
	v_mul_f32_e64 v26, v26, v2
	v_mul_f32_e64 v27, v27, v2
	v_mul_f32_e64 v24, v24, v2
	v_mul_f32_e64 v25, v25, v2
	v_pk_mul_f32 v[22:23], v[22:23], v[2:3] op_sel_hi:[1,0]
	v_pk_mul_f32 v[20:21], v[20:21], v[2:3] op_sel_hi:[1,0]
	v_pk_mul_f32 v[18:19], v[18:19], v[2:3] op_sel_hi:[1,0]
	v_pk_mul_f32 v[16:17], v[16:17], v[2:3] op_sel_hi:[1,0]
	v_sub_f32_e32 v89, v89, v3
	v_sub_f32_e32 v91, v91, v3
	s_waitcnt lgkmcnt(1)
	v_mfma_f32_32x32x16_bf16 v[16:31], v[12:15], v[8:11], v[16:31]
	v_sub_f32_e32 v8, v82, v3
	v_mul_f32_e32 v82, 0x3dd53b94, v8
	v_cvt_pk_bf16_f32 v8, v96, v97
	v_cvt_pk_bf16_f32 v9, v98, v99
	v_cvt_pk_bf16_f32 v10, v100, v101
	v_cvt_pk_bf16_f32 v11, v102, v103
	ds_read2_b64 v[12:15], v106 offset0:164 offset1:166
	v_exp_f32_e32 v82, v82
	s_waitcnt lgkmcnt(1)
	v_mfma_f32_32x32x16_bf16 v[64:79], v[4:7], v[8:11], v[64:79]
	v_sub_f32_e32 v4, v83, v3
	v_mul_f32_e32 v4, 0x3dd53b94, v4
	v_exp_f32_e32 v83, v4
	v_sub_f32_e32 v4, v84, v3
	v_mul_f32_e32 v84, 0x3dd53b94, v4
	ds_read2_b64 v[4:7], v107 offset0:196 offset1:198
	v_exp_f32_e32 v84, v84
	s_waitcnt lgkmcnt(1)
	v_mfma_f32_32x32x16_bf16 v[48:63], v[12:15], v[8:11], v[48:63]
	v_sub_f32_e32 v12, v85, v3
	v_mul_f32_e32 v12, 0x3dd53b94, v12
	v_exp_f32_e32 v85, v12
	v_sub_f32_e32 v12, v86, v3
	v_mul_f32_e32 v86, 0x3dd53b94, v12
	ds_read2_b64 v[12:15], v108 offset0:228 offset1:230
	v_exp_f32_e32 v86, v86
	s_waitcnt lgkmcnt(1)
	v_mfma_f32_32x32x16_bf16 v[32:47], v[4:7], v[8:11], v[32:47]
	v_sub_f32_e32 v4, v87, v3
	v_mul_f32_e32 v4, 0x3dd53b94, v4
	v_exp_f32_e32 v87, v4
	v_sub_f32_e32 v4, v88, v3
	v_mul_f32_e32 v88, 0x3dd53b94, v4
	ds_read2_b64 v[4:7], v105 offset0:136 offset1:138
	v_sub_f32_e32 v93, v93, v3
	s_waitcnt lgkmcnt(1)
	v_mfma_f32_32x32x16_bf16 v[16:31], v[12:15], v[8:11], v[16:31]
	v_cvt_pk_bf16_f32 v8, v80, v81
	v_cvt_pk_bf16_f32 v9, v82, v83
	v_cvt_pk_bf16_f32 v10, v84, v85
	v_cvt_pk_bf16_f32 v11, v86, v87
	ds_read2_b64 v[12:15], v106 offset0:168 offset1:170
	v_exp_f32_e32 v88, v88
	v_mov_b32_e32 v242, v1
	s_waitcnt lgkmcnt(1)
	v_mfma_f32_32x32x16_bf16 v[64:79], v[4:7], v[8:11], v[64:79]
	v_mul_f32_e32 v4, 0x3dd53b94, v89
	v_exp_f32_e32 v89, v4
	v_sub_f32_e32 v4, v90, v3
	v_mul_f32_e32 v4, 0x3dd53b94, v4
	v_exp_f32_e32 v90, v4
	ds_read2_b64 v[4:7], v107 offset0:200 offset1:202
	s_waitcnt lgkmcnt(1)
	v_mfma_f32_32x32x16_bf16 v[48:63], v[12:15], v[8:11], v[48:63]
	v_mul_f32_e32 v12, 0x3dd53b94, v91
	v_exp_f32_e32 v91, v12
	v_sub_f32_e32 v12, v92, v3
	v_mul_f32_e32 v12, 0x3dd53b94, v12
	v_exp_f32_e32 v92, v12
	ds_read2_b64 v[12:15], v108 offset0:232 offset1:234
	s_waitcnt lgkmcnt(1)
	v_mfma_f32_32x32x16_bf16 v[32:47], v[4:7], v[8:11], v[32:47]
	v_mul_f32_e32 v4, 0x3dd53b94, v93
	v_exp_f32_e32 v93, v4
	v_sub_f32_e32 v4, v94, v3
	v_mul_f32_e32 v4, 0x3dd53b94, v4
	v_exp_f32_e32 v94, v4
	ds_read2_b64 v[4:7], v105 offset0:140 offset1:142
	v_sub_f32_e32 v3, v95, v3
	v_mul_f32_e32 v3, 0x3dd53b94, v3
	v_exp_f32_e32 v3, v3
	s_waitcnt lgkmcnt(1)
	v_mfma_f32_32x32x16_bf16 v[16:31], v[12:15], v[8:11], v[16:31]
	ds_read2_b64 v[12:15], v106 offset0:172 offset1:174
	v_cvt_pk_bf16_f32 v8, v88, v89
	v_cvt_pk_bf16_f32 v9, v90, v91
	v_cvt_pk_bf16_f32 v10, v92, v93
	v_cvt_pk_bf16_f32 v11, v94, v3
	s_waitcnt lgkmcnt(1)
	s_nop 0
	v_mfma_f32_32x32x16_bf16 v[64:79], v[4:7], v[8:11], v[64:79]
	v_add_f32_e32 v4, v80, v104
	v_add_f32_e32 v4, v81, v4
	v_add_f32_e32 v4, v82, v4
	v_add_f32_e32 v4, v83, v4
	v_add_f32_e32 v4, v84, v4
	v_add_f32_e32 v80, v85, v4
	ds_read2_b64 v[4:7], v107 offset0:204 offset1:206
	s_waitcnt lgkmcnt(1)
	v_mfma_f32_32x32x16_bf16 v[48:63], v[12:15], v[8:11], v[48:63]
	v_add_f32_e32 v12, v86, v80
	v_add_f32_e32 v12, v87, v12
	v_add_f32_e32 v12, v88, v12
	v_add_f32_e32 v12, v89, v12
	v_add_f32_e32 v12, v90, v12
	v_add_f32_e32 v80, v91, v12
	ds_read2_b64 v[12:15], v108 offset0:236 offset1:238
	s_waitcnt lgkmcnt(1)
	v_mfma_f32_32x32x16_bf16 v[32:47], v[4:7], v[8:11], v[32:47]
	v_add_f32_e32 v4, v92, v80
	v_add_f32_e32 v4, v93, v4
	v_add_f32_e32 v4, v94, v4
	v_add_f32_e32 v3, v3, v4
	v_fmac_f32_e32 v3, v241, v2
	v_mov_b32_e32 v241, v3
	s_waitcnt lgkmcnt(0)
	v_mfma_f32_32x32x16_bf16 v[16:31], v[12:15], v[8:11], v[16:31]
	s_branch .LBB0_421

; #define MFMA(a, b, c) __builtin_amdgcn_mfma_f32_32x32x16_bf16((a), (b), (c), 0, 0, 0)
; template <int DQ, bool MASK>
; DI void attn_phase(const Params& p, unsigned char* smem, float cexp) {
;     ...
;     for (int kt = 0; kt < ntile_block; ++kt) {
;       __syncthreads();
;       {
;         constexpr int CPR = DQ / 8;
; #pragma unroll
;         for (int i = 0; i < DQ / 32; ++i) {
;           int c = tid + 256 * i;
;           int row = c / CPR, cc = c % CPR;
;           uint4 v = *(const uint4*)(Kb + ((size_t)bh * 2048 + kt * 64 + row) * DQ + cc * 8);
;           *(uint4*)(Ks + row * KST + cc * 8) = v;
;         }
; #pragma unroll
;         for (int i = 0; i < 4; ++i) {
;           int c = tid + 256 * i;
;           int d = c >> 3, cc = c & 7;
;           uint4 v = *(const uint4*)(Vt + (((size_t)bh * 32 + kt) * 128 + d) * 64 + cc * 8);
;           uint2* dp = (uint2*)(Vs + d * VST + cc * 8);
;           dp[0] = make_uint2(v.x, v.y);
;           dp[1] = make_uint2(v.z, v.w);
;         }
;       }
;       __syncthreads();
;       if (kt < my_nt) {
;         f32x16 sa[2];
; #pragma unroll
;         for (int u = 0; u < 2; ++u) {
; #pragma unroll
;           for (int i = 0; i < 16; ++i) sa[u][i] = 0.f;
; #pragma unroll
;           for (int s = 0; s < DQ / 16; ++s) {
;             bf16x8 a = *(const bf16x8*)(Ks + (32 * u + r) * KST + 16 * s + 8 * g);
;             sa[u] = MFMA(a, qf[s], sa[u]);
;           }
;         }
;         if (MASK) {
;           u64 mw = mask[tok * 32 + kt] >> (4 * g);
;           const u32 mlo = (u32)mw, mhi = (u32)(mw >> 32);
; #pragma unroll
;           for (int i = 0; i < 16; ++i) {
;             const u32 bit = 1u << ((i & 3) + 8 * (i >> 2));
;             if (!(mlo & bit)) sa[0][i] = -INFINITY;
;             if (!(mhi & bit)) sa[1][i] = -INFINITY;
;           }
.LBB0_1260:
	s_barrier
	v_cmp_lt_i32_e32 vcc, s10, v198
	s_waitcnt vmcnt(7)
	ds_write_b128 v187, v[200:203]
	s_waitcnt vmcnt(6)
	ds_write_b128 v188, v[204:207]
	s_waitcnt vmcnt(5)
	ds_write_b128 v189, v[208:211]
	s_waitcnt vmcnt(4)
	ds_write_b128 v190, v[212:215]
	s_waitcnt vmcnt(3)
	ds_write2_b64 v191, v[226:227], v[228:229] offset1:1
	s_waitcnt vmcnt(2)
	ds_write2_b64 v192, v[230:231], v[232:233] offset1:1
	s_waitcnt vmcnt(1)
	ds_write2_b64 v193, v[234:235], v[236:237] offset1:1
	s_waitcnt vmcnt(0)
	ds_write2_b64 v194, v[238:239], v[240:241] offset1:1
	s_waitcnt lgkmcnt(0)
	s_barrier
	v_lshl_add_u64 v[242:243], s[22:23], 0, v[184:185]
	global_load_dwordx2 v[244:245], v[242:243], off
	s_add_i32 s60, s10, 1
	s_cmp_eq_u32 s60, s25
	s_cselect_b64 s[72:73], s[68:69], s[64:65]
	s_cselect_b64 s[74:75], s[70:71], s[66:67]
	v_lshl_add_u64 v[246:247], s[72:73], 0, v[176:177]
	global_load_dwordx4 v[200:203], v[246:247], off
	v_lshl_add_u64 v[248:249], s[72:73], 0, v[178:179]
	global_load_dwordx4 v[204:207], v[248:249], off
	v_lshl_add_u64 v[246:247], s[72:73], 0, v[180:181]
	global_load_dwordx4 v[208:211], v[246:247], off
	v_lshl_add_u64 v[248:249], s[72:73], 0, v[182:183]
	global_load_dwordx4 v[212:215], v[248:249], off
	v_lshl_add_u64 v[246:247], s[74:75], 0, v[174:175]
	global_load_dwordx4 v[226:229], v[246:247], off
	v_lshl_add_u64 v[248:249], s[74:75], 0, v[172:173]
	global_load_dwordx4 v[230:233], v[248:249], off
	v_lshl_add_u64 v[246:247], s[74:75], 0, v[170:171]
	global_load_dwordx4 v[234:237], v[246:247], off
	v_lshl_add_u64 v[248:249], s[74:75], 0, v[168:169]
	global_load_dwordx4 v[238:241], v[248:249], off
	s_and_saveexec_b64 s[16:17], vcc
	s_cbranch_execz .LBB0_1259
	ds_read_b128 v[4:7], v195
	ds_read_b128 v[8:11], v195 offset:8704
	ds_read_b128 v[12:15], v195 offset:32
	ds_read_b128 v[250:253], v195 offset:8736
	s_waitcnt lgkmcnt(3)
	v_mfma_f32_32x32x16_bf16 v[80:95], v[4:7], v[112:115], 0
	ds_read_b128 v[4:7], v195 offset:64
	s_waitcnt lgkmcnt(3)
	v_mfma_f32_32x32x16_bf16 v[96:111], v[8:11], v[112:115], 0
	ds_read_b128 v[8:11], v195 offset:8768
	s_waitcnt lgkmcnt(3)
	v_mfma_f32_32x32x16_bf16 v[80:95], v[12:15], v[116:119], v[80:95]
	ds_read_b128 v[12:15], v195 offset:96
	s_waitcnt lgkmcnt(3)
	v_mfma_f32_32x32x16_bf16 v[96:111], v[250:253], v[116:119], v[96:111]
	ds_read_b128 v[250:253], v195 offset:8800
	s_waitcnt lgkmcnt(3)
	v_mfma_f32_32x32x16_bf16 v[80:95], v[4:7], v[120:123], v[80:95]
	ds_read_b128 v[4:7], v195 offset:128
	s_waitcnt lgkmcnt(3)
	v_mfma_f32_32x32x16_bf16 v[96:111], v[8:11], v[120:123], v[96:111]
	ds_read_b128 v[8:11], v195 offset:8832
	s_waitcnt lgkmcnt(3)
	v_mfma_f32_32x32x16_bf16 v[80:95], v[12:15], v[124:127], v[80:95]
	ds_read_b128 v[12:15], v195 offset:160
	s_waitcnt lgkmcnt(3)
	v_mfma_f32_32x32x16_bf16 v[96:111], v[250:253], v[124:127], v[96:111]
	ds_read_b128 v[250:253], v195 offset:8864
	s_waitcnt lgkmcnt(3)
	v_mfma_f32_32x32x16_bf16 v[80:95], v[4:7], v[128:131], v[80:95]
	ds_read_b128 v[4:7], v195 offset:192
	s_waitcnt lgkmcnt(3)
	v_mfma_f32_32x32x16_bf16 v[96:111], v[8:11], v[128:131], v[96:111]
	ds_read_b128 v[8:11], v195 offset:8896
	s_waitcnt lgkmcnt(3)
	v_mfma_f32_32x32x16_bf16 v[80:95], v[12:15], v[132:135], v[80:95]
	ds_read_b128 v[12:15], v195 offset:224
	s_waitcnt lgkmcnt(3)
	v_mfma_f32_32x32x16_bf16 v[96:111], v[250:253], v[132:135], v[96:111]
	ds_read_b128 v[250:253], v195 offset:8928
	s_waitcnt lgkmcnt(3)
	v_mfma_f32_32x32x16_bf16 v[80:95], v[4:7], v[136:139], v[80:95]
	s_waitcnt lgkmcnt(2)
	v_mfma_f32_32x32x16_bf16 v[96:111], v[8:11], v[136:139], v[96:111]
	s_waitcnt lgkmcnt(1)
	v_mfma_f32_32x32x16_bf16 v[80:95], v[12:15], v[140:143], v[80:95]
	s_waitcnt lgkmcnt(0)
	v_mfma_f32_32x32x16_bf16 v[96:111], v[250:253], v[140:143], v[96:111]
	s_waitcnt vmcnt(8)
	v_mov_b32_e32 v4, v244
	v_mov_b32_e32 v5, v245
	v_lshrrev_b32_e32 v3, v148, v4
	s_nop 7
	s_nop 1
	v_lshrrev_b64 v[12:13], v148, v[4:5]
	v_and_b32_e32 v3, 1, v3
	v_cmp_eq_u32_e32 vcc, 1, v3
	v_and_b32_e32 v3, 1, v13
	s_nop 0
	v_cndmask_b32_e32 v14, v197, v80, vcc
	v_cmp_eq_u32_e32 vcc, 1, v3
	v_and_b32_e32 v3, 2, v12
	s_nop 3
	v_cndmask_b32_e32 v10, v197, v96, vcc
	v_cmp_ne_u32_e32 vcc, 0, v3
	v_and_b32_e32 v3, 2, v13
	s_nop 0
	v_cndmask_b32_e32 v11, v197, v81, vcc
	v_cmp_ne_u32_e32 vcc, 0, v3
	v_and_b32_e32 v3, 4, v12
	s_nop 0
	v_cndmask_b32_e32 v15, v197, v97, vcc
	v_cmp_ne_u32_e32 vcc, 0, v3
	v_and_b32_e32 v3, 4, v13
	s_nop 0
	v_cndmask_b32_e32 v80, v197, v82, vcc
	v_cmp_ne_u32_e32 vcc, 0, v3
	v_and_b32_e32 v3, 8, v12
	s_nop 0
	v_cndmask_b32_e32 v96, v197, v98, vcc
	v_cmp_ne_u32_e32 vcc, 0, v3
	v_and_b32_e32 v3, 8, v13
	s_nop 0
	v_cndmask_b32_e32 v81, v197, v83, vcc
	v_cmp_ne_u32_e32 vcc, 0, v3
	v_and_b32_e32 v3, 0x100, v12
	s_nop 0
	v_cndmask_b32_e32 v97, v197, v99, vcc
	v_cmp_ne_u32_e32 vcc, 0, v3
	v_and_b32_e32 v3, 0x100, v13
	s_nop 0
	v_cndmask_b32_e32 v82, v197, v84, vcc
	v_cmp_ne_u32_e32 vcc, 0, v3
	v_and_b32_e32 v3, 0x200, v12
	s_nop 0
	v_cndmask_b32_e32 v98, v197, v100, vcc
	v_cmp_ne_u32_e32 vcc, 0, v3
	v_and_b32_e32 v3, 0x200, v13
	s_nop 0
	v_cndmask_b32_e32 v83, v197, v85, vcc
	v_cmp_ne_u32_e32 vcc, 0, v3
	v_and_b32_e32 v3, 0x400, v12
	s_nop 0
	v_cndmask_b32_e32 v99, v197, v101, vcc
	v_cmp_ne_u32_e32 vcc, 0, v3
	v_and_b32_e32 v3, 0x400, v13
	s_nop 0
	v_cndmask_b32_e32 v84, v197, v86, vcc
	v_cmp_ne_u32_e32 vcc, 0, v3
	v_and_b32_e32 v3, 0x800, v12
	s_nop 0
	v_cndmask_b32_e32 v100, v197, v102, vcc
	v_cmp_ne_u32_e32 vcc, 0, v3
	v_and_b32_e32 v3, 0x800, v13
	s_nop 0
	v_cndmask_b32_e32 v85, v197, v87, vcc
	v_cmp_ne_u32_e32 vcc, 0, v3
	v_and_b32_e32 v3, 0x10000, v12
	s_nop 0
	v_cndmask_b32_e32 v101, v197, v103, vcc
	v_cmp_ne_u32_e32 vcc, 0, v3
; template <int DQ, bool MASK>
; DI void attn_phase(const Params& p, unsigned char* smem, float cexp) {
;     ...
;         if (MASK) {
;           u64 mw = mask[tok * 32 + kt] >> (4 * g);
;           const u32 mlo = (u32)mw, mhi = (u32)(mw >> 32);
; #pragma unroll
;           for (int i = 0; i < 16; ++i) {
;             const u32 bit = 1u << ((i & 3) + 8 * (i >> 2));
;             if (!(mlo & bit)) sa[0][i] = -INFINITY;
;             if (!(mhi & bit)) sa[1][i] = -INFINITY;
;           }
;         }
;         float mx = -INFINITY;
; #pragma unroll
;         for (int u = 0; u < 2; ++u)
; #pragma unroll
;           for (int i = 0; i < 16; ++i) mx = fmaxf(mx, sa[u][i]);
;         mx = fmaxf(mx, __shfl_xor(mx, 32));
;         float mnew = fmaxf(m, mx);
;         float muse = (mnew == -INFINITY) ? 0.f : mnew;
;         float alpha = __builtin_amdgcn_exp2f((m - muse) * cexp);
;         m = mnew;
;         float ps = 0.f;
; #pragma unroll
;         for (int u = 0; u < 2; ++u)
; #pragma unroll
;           for (int i = 0; i < 16; ++i) {
;             float pv = __builtin_amdgcn_exp2f((sa[u][i] - muse) * cexp);
;             ps += pv;
;             sa[u][i] = pv;
;           }
;         l = l * alpha + ps;
; #pragma unroll
;         for (int j = 0; j < 4; ++j)
; #pragma unroll
;           for (int i = 0; i < 16; ++i) o[j][i] *= alpha;
	v_and_b32_e32 v3, 0x10000, v13
	s_nop 0
	v_cndmask_b32_e32 v86, v197, v88, vcc
	v_cmp_ne_u32_e32 vcc, 0, v3
	v_and_b32_e32 v3, 0x20000, v12
	s_nop 0
	v_cndmask_b32_e32 v88, v197, v104, vcc
	v_cmp_ne_u32_e32 vcc, 0, v3
	v_and_b32_e32 v3, 0x20000, v13
	s_nop 0
	v_cndmask_b32_e32 v87, v197, v89, vcc
	v_cmp_ne_u32_e32 vcc, 0, v3
	v_and_b32_e32 v3, 0x40000, v12
	s_nop 0
	v_cndmask_b32_e32 v89, v197, v105, vcc
	v_cmp_ne_u32_e32 vcc, 0, v3
	v_and_b32_e32 v3, 0x40000, v13
	s_nop 0
	v_cndmask_b32_e32 v90, v197, v90, vcc
	v_cmp_ne_u32_e32 vcc, 0, v3
	v_and_b32_e32 v3, 0x80000, v12
	s_nop 0
	v_cndmask_b32_e32 v8, v197, v106, vcc
	v_cmp_ne_u32_e32 vcc, 0, v3
	v_and_b32_e32 v3, 0x80000, v13
	s_nop 0
	v_cndmask_b32_e32 v91, v197, v91, vcc
	v_cmp_ne_u32_e32 vcc, 0, v3
	v_and_b32_e32 v3, 0x1000000, v12
	s_nop 0
	v_cndmask_b32_e32 v9, v197, v107, vcc
	v_cmp_ne_u32_e32 vcc, 0, v3
	v_and_b32_e32 v3, 0x1000000, v13
	s_nop 0
	v_cndmask_b32_e32 v92, v197, v92, vcc
	v_cmp_ne_u32_e32 vcc, 0, v3
	v_and_b32_e32 v3, 0x2000000, v12
	s_nop 0
	v_cndmask_b32_e32 v6, v197, v108, vcc
	v_cmp_ne_u32_e32 vcc, 0, v3
	v_and_b32_e32 v3, 0x2000000, v13
	s_nop 0
	v_cndmask_b32_e32 v93, v197, v93, vcc
	v_cmp_ne_u32_e32 vcc, 0, v3
	v_and_b32_e32 v3, 0x4000000, v12
	s_nop 0
	v_cndmask_b32_e32 v7, v197, v109, vcc
	v_cmp_ne_u32_e32 vcc, 0, v3
	v_and_b32_e32 v3, 0x4000000, v13
	s_nop 0
	v_cndmask_b32_e32 v94, v197, v94, vcc
	v_cmp_ne_u32_e32 vcc, 0, v3
	v_and_b32_e32 v3, 0x8000000, v12
	s_nop 0
	v_cndmask_b32_e32 v4, v197, v110, vcc
	v_cmp_ne_u32_e32 vcc, 0, v3
	v_and_b32_e32 v3, 0x8000000, v13
	v_add_u32_e32 v110, 0x4000, v196
	v_cndmask_b32_e32 v12, v197, v95, vcc
	v_cmp_ne_u32_e32 vcc, 0, v3
	v_max3_f32 v3, v14, s5, v11
	v_max3_f32 v3, v3, v80, v81
	v_max3_f32 v3, v3, v82, v83
	v_max3_f32 v3, v3, v84, v85
	v_max3_f32 v3, v3, v86, v87
	v_max3_f32 v3, v3, v90, v91
	v_max3_f32 v3, v3, v92, v93
	v_max3_f32 v3, v3, v94, v12
	v_max3_f32 v3, v3, v10, v15
	v_max3_f32 v3, v3, v96, v97
	v_max3_f32 v3, v3, v98, v99
	v_max3_f32 v3, v3, v100, v101
	v_max3_f32 v3, v3, v88, v89
	v_max3_f32 v3, v3, v8, v9
	v_cndmask_b32_e32 v5, v197, v111, vcc
	v_max3_f32 v3, v3, v6, v7
	v_max3_f32 v3, v3, v4, v5
	v_mov_b32_e32 v13, v3
	s_nop 1
	v_permlane32_swap_b32_e32 v3, v13
	v_add_u32_e32 v111, 0x7000, v196
	s_waitcnt lgkmcnt(0)
	v_max3_f32 v3, v2, v3, v13
	v_cmp_neq_f32_e32 vcc, s5, v3
	s_nop 1
	v_cndmask_b32_e32 v95, 0, v3, vcc
	v_sub_f32_e32 v11, v11, v95
	v_sub_f32_e32 v13, v14, v95
	v_mul_f32_e32 v11, 0x3e0293ee, v11
	v_mul_f32_e32 v13, 0x3e0293ee, v13
	v_exp_f32_e32 v102, v11
	v_sub_f32_e32 v11, v80, v95
	v_exp_f32_e32 v14, v13
	v_mul_f32_e32 v11, 0x3e0293ee, v11
	v_exp_f32_e32 v103, v11
	v_sub_f32_e32 v11, v81, v95
	v_mul_f32_e32 v11, 0x3e0293ee, v11
	v_exp_f32_e32 v81, v11
	v_sub_f32_e32 v11, v82, v95
	v_add_f32_e32 v13, 0, v14
	v_mul_f32_e32 v11, 0x3e0293ee, v11
	v_exp_f32_e32 v82, v11
	v_add_f32_e32 v11, v102, v13
	v_sub_f32_e32 v13, v83, v95
	v_mul_f32_e32 v13, 0x3e0293ee, v13
	v_exp_f32_e32 v83, v13
	v_sub_f32_e32 v13, v84, v95
	v_mul_f32_e32 v13, 0x3e0293ee, v13
	v_exp_f32_e32 v84, v13
	v_sub_f32_e32 v13, v85, v95
	v_mul_f32_e32 v13, 0x3e0293ee, v13
	v_exp_f32_e32 v85, v13
	v_sub_f32_e32 v13, v86, v95
	v_mul_f32_e32 v13, 0x3e0293ee, v13
	v_exp_f32_e32 v104, v13
	v_sub_f32_e32 v13, v87, v95
	v_mul_f32_e32 v13, 0x3e0293ee, v13
	v_add_f32_e32 v11, v103, v11
	v_exp_f32_e32 v105, v13
	v_sub_f32_e32 v13, v90, v95
	v_add_f32_e32 v11, v81, v11
	v_mul_f32_e32 v13, 0x3e0293ee, v13
	v_add_f32_e32 v11, v82, v11
	v_exp_f32_e32 v90, v13
	v_sub_f32_e32 v13, v91, v95
	v_add_f32_e32 v11, v83, v11
	v_mul_f32_e32 v13, 0x3e0293ee, v13
	v_add_f32_e32 v11, v84, v11
	v_exp_f32_e32 v91, v13
	v_sub_f32_e32 v13, v92, v95
	v_add_f32_e32 v11, v85, v11
	v_mul_f32_e32 v13, 0x3e0293ee, v13
	v_add_f32_e32 v11, v104, v11
	v_exp_f32_e32 v92, v13
	v_add_f32_e32 v11, v105, v11
	v_add_f32_e32 v11, v90, v11
	v_add_f32_e32 v11, v91, v11
	v_add_f32_e32 v106, v92, v11
	v_sub_f32_e32 v11, v93, v95
	v_mul_f32_e32 v11, 0x3e0293ee, v11
	v_exp_f32_e32 v93, v11
	v_sub_f32_e32 v11, v94, v95
	v_sub_f32_e32 v10, v10, v95
	v_mul_f32_e32 v11, 0x3e0293ee, v11
	v_mul_f32_e32 v10, 0x3e0293ee, v10
	v_exp_f32_e32 v94, v11
	v_sub_f32_e32 v11, v12, v95
	v_exp_f32_e32 v108, v10
	v_sub_f32_e32 v10, v15, v95
	v_mul_f32_e32 v11, 0x3e0293ee, v11
	v_mul_f32_e32 v10, 0x3e0293ee, v10
	v_exp_f32_e32 v107, v11
	v_exp_f32_e32 v109, v10
	ds_read2_b64 v[10:13], v110 offset0:128 offset1:130
	v_sub_f32_e32 v2, v2, v95
	v_mul_f32_e32 v2, 0x3e0293ee, v2
	v_exp_f32_e32 v2, v2
	v_cvt_pk_bf16_f32 v80, v14, v102
	v_add_u32_e32 v102, 0x5000, v196
	v_cvt_pk_bf16_f32 v81, v103, v81
	v_pk_mul_f32 v[78:79], v[78:79], v[2:3] op_sel_hi:[1,0]
	v_pk_mul_f32 v[76:77], v[76:77], v[2:3] op_sel_hi:[1,0]
	v_pk_mul_f32 v[74:75], v[74:75], v[2:3] op_sel_hi:[1,0]
	v_pk_mul_f32 v[72:73], v[72:73], v[2:3] op_sel_hi:[1,0]
	v_pk_mul_f32 v[70:71], v[70:71], v[2:3] op_sel_hi:[1,0]
	v_pk_mul_f32 v[68:69], v[68:69], v[2:3] op_sel_hi:[1,0]
	v_pk_mul_f32 v[66:67], v[66:67], v[2:3] op_sel_hi:[1,0]
	v_pk_mul_f32 v[64:65], v[64:65], v[2:3] op_sel_hi:[1,0]
	v_cvt_pk_bf16_f32 v82, v82, v83
	v_cvt_pk_bf16_f32 v83, v84, v85
	ds_read2_b64 v[84:87], v102 offset0:160 offset1:162
	v_add_u32_e32 v103, 0x6000, v196
	s_waitcnt lgkmcnt(1)
; #define MFMA(a, b, c) __builtin_amdgcn_mfma_f32_32x32x16_bf16((a), (b), (c), 0, 0, 0)
; template <int DQ, bool MASK>
; DI void attn_phase(const Params& p, unsigned char* smem, float cexp) {
;     ...
; #pragma unroll
;         for (int u = 0; u < 2; ++u)
; #pragma unroll
;           for (int i = 0; i < 16; ++i) {
;             float pv = __builtin_amdgcn_exp2f((sa[u][i] - muse) * cexp);
;             ps += pv;
;             sa[u][i] = pv;
;           }
;         l = l * alpha + ps;
; #pragma unroll
;         for (int j = 0; j < 4; ++j)
; #pragma unroll
;           for (int i = 0; i < 16; ++i) o[j][i] *= alpha;
; #pragma unroll
;         for (int u = 0; u < 2; ++u)
; #pragma unroll
;           for (int s2 = 0; s2 < 2; ++s2) {
;             uint4 pp;
;             pp.x = pack2(sa[u][8 * s2 + 0], sa[u][8 * s2 + 1]);
;             pp.y = pack2(sa[u][8 * s2 + 2], sa[u][8 * s2 + 3]);
;             pp.z = pack2(sa[u][8 * s2 + 4], sa[u][8 * s2 + 5]);
;             pp.w = pack2(sa[u][8 * s2 + 6], sa[u][8 * s2 + 7]);
;             bf16x8 pf = __builtin_bit_cast(bf16x8, pp);
; #pragma unroll
;             for (int dt = 0; dt < 4; ++dt) {
;               const bf16* vp = Vs + (32 * dt + r) * VST + 32 * u + 16 * s2 + 4 * g;
;               s16x4 lo = *(const s16x4*)vp;
;               s16x4 hi = *(const s16x4*)(vp + 8);
;               bf16x8 vf = __builtin_shufflevector(lo, hi, 0, 1, 2, 3, 4, 5, 6, 7);
;               o[dt] = MFMA(vf, pf, o[dt]);
;             }
;           }
	v_mfma_f32_32x32x16_bf16 v[64:79], v[10:13], v[80:83], v[64:79]
	ds_read2_b64 v[10:13], v103 offset0:192 offset1:194
	v_mul_f32_e64 v62, v62, v2
	v_mul_f32_e64 v63, v63, v2
	v_mul_f32_e64 v60, v60, v2
	v_mul_f32_e64 v61, v61, v2
	v_pk_mul_f32 v[58:59], v[58:59], v[2:3] op_sel_hi:[1,0]
	v_pk_mul_f32 v[56:57], v[56:57], v[2:3] op_sel_hi:[1,0]
	v_pk_mul_f32 v[54:55], v[54:55], v[2:3] op_sel_hi:[1,0]
	v_pk_mul_f32 v[52:53], v[52:53], v[2:3] op_sel_hi:[1,0]
	v_pk_mul_f32 v[50:51], v[50:51], v[2:3] op_sel_hi:[1,0]
	v_pk_mul_f32 v[48:49], v[48:49], v[2:3] op_sel_hi:[1,0]
	v_pk_mul_f32 v[46:47], v[46:47], v[2:3] op_sel_hi:[1,0]
	v_pk_mul_f32 v[44:45], v[44:45], v[2:3] op_sel_hi:[1,0]
	v_pk_mul_f32 v[42:43], v[42:43], v[2:3] op_sel_hi:[1,0]
	v_pk_mul_f32 v[40:41], v[40:41], v[2:3] op_sel_hi:[1,0]
	v_pk_mul_f32 v[38:39], v[38:39], v[2:3] op_sel_hi:[1,0]
	s_waitcnt lgkmcnt(1)
	v_mfma_f32_32x32x16_bf16 v[48:63], v[84:87], v[80:83], v[48:63]
	v_mul_f32_e64 v36, v36, v2
	v_mul_f32_e64 v37, v37, v2
	v_mul_f32_e64 v34, v34, v2
	v_mul_f32_e64 v35, v35, v2
	v_mul_f32_e64 v32, v32, v2
	v_mul_f32_e64 v33, v33, v2
	ds_read2_b64 v[84:87], v111 offset0:224 offset1:226
	v_pk_mul_f32 v[30:31], v[30:31], v[2:3] op_sel_hi:[1,0]
	v_pk_mul_f32 v[28:29], v[28:29], v[2:3] op_sel_hi:[1,0]
	v_pk_mul_f32 v[26:27], v[26:27], v[2:3] op_sel_hi:[1,0]
	s_waitcnt lgkmcnt(1)
	v_mfma_f32_32x32x16_bf16 v[32:47], v[10:13], v[80:83], v[32:47]
	ds_read2_b64 v[10:13], v110 offset0:132 offset1:134
	v_mul_f32_e64 v24, v24, v2
	v_mul_f32_e64 v25, v25, v2
	v_mul_f32_e64 v22, v22, v2
	v_mul_f32_e64 v23, v23, v2
	v_pk_mul_f32 v[20:21], v[20:21], v[2:3] op_sel_hi:[1,0]
	v_pk_mul_f32 v[18:19], v[18:19], v[2:3] op_sel_hi:[1,0]
	v_pk_mul_f32 v[16:17], v[16:17], v[2:3] op_sel_hi:[1,0]
	v_sub_f32_e32 v14, v96, v95
	v_mul_f32_e32 v14, 0x3e0293ee, v14
	s_waitcnt lgkmcnt(1)
	v_mfma_f32_32x32x16_bf16 v[16:31], v[84:87], v[80:83], v[16:31]
	v_cvt_pk_bf16_f32 v80, v104, v105
	v_cvt_pk_bf16_f32 v81, v90, v91
	v_cvt_pk_bf16_f32 v82, v92, v93
	v_cvt_pk_bf16_f32 v83, v94, v107
	ds_read2_b64 v[84:87], v102 offset0:164 offset1:166
	v_exp_f32_e32 v90, v14
	v_sub_f32_e32 v8, v8, v95
	s_waitcnt lgkmcnt(1)
	v_mfma_f32_32x32x16_bf16 v[64:79], v[10:13], v[80:83], v[64:79]
	v_sub_f32_e32 v10, v97, v95
	v_mul_f32_e32 v10, 0x3e0293ee, v10
	v_exp_f32_e32 v91, v10
	v_sub_f32_e32 v10, v98, v95
	v_mul_f32_e32 v14, 0x3e0293ee, v10
	ds_read2_b64 v[10:13], v103 offset0:196 offset1:198
	v_exp_f32_e32 v92, v14
	s_waitcnt lgkmcnt(1)
	v_mfma_f32_32x32x16_bf16 v[48:63], v[84:87], v[80:83], v[48:63]
	v_sub_f32_e32 v14, v99, v95
	ds_read2_b64 v[84:87], v111 offset0:228 offset1:230
	v_mul_f32_e32 v14, 0x3e0293ee, v14
	v_exp_f32_e32 v96, v14
	v_sub_f32_e32 v14, v100, v95
	v_mul_f32_e32 v14, 0x3e0293ee, v14
	v_exp_f32_e32 v97, v14
	s_waitcnt lgkmcnt(1)
	v_mfma_f32_32x32x16_bf16 v[32:47], v[10:13], v[80:83], v[32:47]
	v_sub_f32_e32 v10, v101, v95
	v_mul_f32_e32 v10, 0x3e0293ee, v10
	v_exp_f32_e32 v98, v10
	v_sub_f32_e32 v10, v88, v95
	v_mul_f32_e32 v14, 0x3e0293ee, v10
	ds_read2_b64 v[10:13], v110 offset0:136 offset1:138
	v_exp_f32_e32 v88, v14
	s_waitcnt lgkmcnt(1)
	v_mfma_f32_32x32x16_bf16 v[16:31], v[84:87], v[80:83], v[16:31]
	ds_read2_b64 v[84:87], v102 offset0:168 offset1:170
	v_sub_f32_e32 v14, v89, v95
	v_cvt_pk_bf16_f32 v80, v108, v109
	v_cvt_pk_bf16_f32 v81, v90, v91
	v_cvt_pk_bf16_f32 v82, v92, v96
	v_cvt_pk_bf16_f32 v83, v97, v98
	v_mul_f32_e32 v8, 0x3e0293ee, v8
	v_exp_f32_e32 v99, v8
	s_waitcnt lgkmcnt(1)
	v_mfma_f32_32x32x16_bf16 v[64:79], v[10:13], v[80:83], v[64:79]
	v_mul_f32_e32 v10, 0x3e0293ee, v14
	v_exp_f32_e32 v89, v10
	v_sub_f32_e32 v12, v9, v95
	ds_read2_b64 v[8:11], v103 offset0:200 offset1:202
	v_mul_f32_e32 v12, 0x3e0293ee, v12
	v_sub_f32_e32 v6, v6, v95
	v_mul_f32_e32 v6, 0x3e0293ee, v6
	s_waitcnt lgkmcnt(1)
	v_mfma_f32_32x32x16_bf16 v[48:63], v[84:87], v[80:83], v[48:63]
	v_exp_f32_e32 v84, v12
	ds_read2_b64 v[12:15], v111 offset0:232 offset1:234
	v_exp_f32_e32 v85, v6
	v_sub_f32_e32 v6, v7, v95
	v_sub_f32_e32 v4, v4, v95
	v_mul_f32_e32 v6, 0x3e0293ee, v6
	v_mul_f32_e32 v4, 0x3e0293ee, v4
	s_waitcnt lgkmcnt(1)
	v_mfma_f32_32x32x16_bf16 v[32:47], v[8:11], v[80:83], v[32:47]
	v_exp_f32_e32 v86, v6
	v_exp_f32_e32 v87, v4
	v_sub_f32_e32 v8, v5, v95
	ds_read2_b64 v[4:7], v110 offset0:140 offset1:142
	v_mul_f32_e32 v8, 0x3e0293ee, v8
	v_cvt_pk_bf16_f32 v9, v99, v84
	v_cvt_pk_bf16_f32 v10, v85, v86
	s_waitcnt lgkmcnt(1)
	v_mfma_f32_32x32x16_bf16 v[16:31], v[12:15], v[80:83], v[16:31]
	v_exp_f32_e32 v80, v8
	ds_read2_b64 v[12:15], v102 offset0:172 offset1:174
	v_cvt_pk_bf16_f32 v8, v88, v89
	v_cvt_pk_bf16_f32 v11, v87, v80
	s_waitcnt lgkmcnt(1)
	s_nop 0
	v_mfma_f32_32x32x16_bf16 v[64:79], v[4:7], v[8:11], v[64:79]
	v_add_f32_e32 v4, v93, v106
	v_add_f32_e32 v4, v94, v4
	v_add_f32_e32 v4, v107, v4
	v_add_f32_e32 v4, v108, v4
	v_add_f32_e32 v4, v109, v4
	v_add_f32_e32 v81, v90, v4
	ds_read2_b64 v[4:7], v103 offset0:204 offset1:206
	s_waitcnt lgkmcnt(1)
	v_mfma_f32_32x32x16_bf16 v[48:63], v[12:15], v[8:11], v[48:63]
	v_add_f32_e32 v12, v91, v81
	v_add_f32_e32 v12, v92, v12
	v_add_f32_e32 v12, v96, v12
	v_add_f32_e32 v12, v97, v12
	v_add_f32_e32 v12, v98, v12
	v_add_f32_e32 v81, v88, v12
	ds_read2_b64 v[12:15], v111 offset0:236 offset1:238
	s_waitcnt lgkmcnt(1)
	v_mfma_f32_32x32x16_bf16 v[32:47], v[4:7], v[8:11], v[32:47]
	v_add_f32_e32 v4, v89, v81
	v_add_f32_e32 v4, v99, v4
	v_add_f32_e32 v4, v84, v4
	v_add_f32_e32 v4, v85, v4
	v_add_f32_e32 v4, v86, v4
	v_add_f32_e32 v4, v87, v4
	v_add_f32_e32 v4, v80, v4
	s_waitcnt lgkmcnt(0)
	v_mfma_f32_32x32x16_bf16 v[16:31], v[12:15], v[8:11], v[16:31]
	v_fmac_f32_e32 v4, v1, v2
	v_mov_b32_e32 v1, v4
	v_mov_b32_e32 v2, v3
	s_branch .LBB0_1259
